# v019 plus hand-written residual-GEMM epilogue: base loads 4 row-groups deep (16 loads in flight), exact vmcnt counts, saddr addressing
# speedup vs baseline: 1.0003x; 1.0003x over previous
;     __device__ __forceinline__ void operator()(const f32x4 (&acc)[2][2][4][2], const Unit& u, int wr, int wc, int fr, int fq) const {
;         const int row0 = u.pm * BM + wr * 64 + fr; const int col0 = u.pn * BM + wc * 32 + 8 * fq;
;         f32x4 nb[4];
;         { const size_t off = (size_t)row0 * XD + col0; nb[0] = *(const f32x4*)(base + off); nb[1] = *(const f32x4*)(base + off + 4); nb[2] = *(const f32x4*)(base + off + HALF); nb[3] = *(const f32x4*)(base + off + HALF + 4); }
; #pragma unroll
;         for (int it = 0; it < 8; ++it) {
;             const int ai = it >> 2, m = it & 3;
;             const int row = row0 + ai * HALF + m * 16; float sq = 0.f;
;             const f32x4 cb0 = nb[0], cb1 = nb[1], cb2 = nb[2], cb3 = nb[3];
;             if (it < 7) { const size_t offn = (size_t)(row0 + ((it + 1) >> 2) * HALF + ((it + 1) & 3) * 16) * XD + col0;
;                 nb[0] = *(const f32x4*)(base + offn); nb[1] = *(const f32x4*)(base + offn + 4); nb[2] = *(const f32x4*)(base + offn + HALF); nb[3] = *(const f32x4*)(base + offn + HALF + 4); }
; #pragma unroll
;             for (int bj = 0; bj < 2; ++bj) {
;                 const size_t off = (size_t)row * XD + col0 + bj * HALF;
;                 const f32x4 v0 = acc[ai][bj][m][0] + (bj ? cb2 : cb0), v1 = acc[ai][bj][m][1] + (bj ? cb3 : cb1);
;                 if (out) { __builtin_nontemporal_store(v0, (f32x4*)(out + off)); __builtin_nontemporal_store(v1, (f32x4*)(out + off + 4)); }
;                 u32x4 w; w.x = cvt_pk_bf16(v0[0], v0[1]); w.y = cvt_pk_bf16(v0[2], v0[3]); w.z = cvt_pk_bf16(v1[0], v1[1]); w.w = cvt_pk_bf16(v1[2], v1[3]);
;                 if (xb) *(u32x4*)(xb + off) = w;
;                 sq += (v0[0] * v0[0] + v0[1] * v0[1]) + (v0[2] * v0[2] + v0[3] * v0[3]) + (v1[0] * v1[0] + v1[1] * v1[1]) + (v1[2] * v1[2] + v1[3] * v1[3]);
;             }
;             { const unsigned u1 = __float_as_uint(sq); auto r1 = __builtin_amdgcn_permlane16_swap(u1, u1, false, false); sq = __uint_as_float(r1[0]) + __uint_as_float(r1[1]);
;               const unsigned u2 = __float_as_uint(sq); auto r2 = __builtin_amdgcn_permlane32_swap(u2, u2, false, false); sq = __uint_as_float(r2[0]) + __uint_as_float(r2[1]); }
;             if (fq == 0) atomicAdd(ssn + row, (unsigned long long)(sq * SS_SCALE));
.LBB0_1430:
	s_cmp_eq_u64 s[50:51], 0
	s_cbranch_scc1 .Lepires_orig
	v_lshl_add_u32 v166, s93, 8, v184
	v_lshl_or_b32 v168, s92, 8, v186
	v_lshlrev_b32_e32 v164, 13, v166
	v_lshlrev_b32_e32 v165, 3, v166
	v_lshl_add_u32 v164, v168, 2, v164
	global_load_dwordx4 v[190:193], v164, s[14:15]
	global_load_dwordx4 v[194:197], v164, s[14:15] offset:16
	global_load_dwordx4 v[198:201], v164, s[14:15] offset:512
	global_load_dwordx4 v[202:205], v164, s[14:15] offset:528
	v_add_u32_e32 v180, 0x20000, v164
	global_load_dwordx4 v[206:209], v180, s[14:15]
	global_load_dwordx4 v[210:213], v180, s[14:15] offset:16
	global_load_dwordx4 v[214:217], v180, s[14:15] offset:512
	global_load_dwordx4 v[218:221], v180, s[14:15] offset:528
	v_add_u32_e32 v180, 0x40000, v164
	global_load_dwordx4 v[130:133], v180, s[14:15]
	global_load_dwordx4 v[134:137], v180, s[14:15] offset:16
	global_load_dwordx4 v[138:141], v180, s[14:15] offset:512
	global_load_dwordx4 v[142:145], v180, s[14:15] offset:528
	v_add_u32_e32 v180, 0x60000, v164
	global_load_dwordx4 v[146:149], v180, s[14:15]
	global_load_dwordx4 v[150:153], v180, s[14:15] offset:16
	global_load_dwordx4 v[232:235], v180, s[14:15] offset:512
	global_load_dwordx4 v[236:239], v180, s[14:15] offset:528
	s_waitcnt vmcnt(12)
	v_pk_add_f32 v[126:127], v[126:127], v[190:191]
	v_pk_add_f32 v[128:129], v[128:129], v[192:193]
	v_pk_add_f32 v[122:123], v[122:123], v[194:195]
	v_pk_add_f32 v[124:125], v[124:125], v[196:197]
	v_pk_add_f32 v[118:119], v[118:119], v[198:199]
	v_pk_add_f32 v[120:121], v[120:121], v[200:201]
	v_pk_add_f32 v[114:115], v[114:115], v[202:203]
	v_pk_add_f32 v[116:117], v[116:117], v[204:205]
	v_mov_b32_e32 v166, v164
	v_lshrrev_b32_e32 v167, 1, v166
	global_store_dwordx4 v166, v[126:129], s[30:31] nt
	global_store_dwordx4 v166, v[122:125], s[30:31] offset:16 nt
	v_cvt_pk_bf16_f32 v190, v126, v127
	v_cvt_pk_bf16_f32 v191, v128, v129
	v_cvt_pk_bf16_f32 v192, v122, v123
	v_cvt_pk_bf16_f32 v193, v124, v125
	global_store_dwordx4 v167, v[190:193], s[20:21]
	global_store_dwordx4 v166, v[118:121], s[30:31] offset:512 nt
	global_store_dwordx4 v166, v[114:117], s[30:31] offset:528 nt
	v_mul_f32_e32 v198, v127, v127
	v_fmac_f32_e32 v198, v126, v126
	v_mul_f32_e32 v199, v129, v129
	v_fmac_f32_e32 v199, v128, v128
	v_mul_f32_e32 v200, v123, v123
	v_add_f32_e32 v198, v198, v199
	v_fmac_f32_e32 v200, v122, v122
	v_add_f32_e32 v198, v198, v200
	v_mul_f32_e32 v200, v125, v125
	v_fmac_f32_e32 v200, v124, v124
	v_add_f32_e32 v201, v200, v198
	v_cvt_pk_bf16_f32 v194, v118, v119
	v_cvt_pk_bf16_f32 v195, v120, v121
	v_cvt_pk_bf16_f32 v196, v114, v115
	v_cvt_pk_bf16_f32 v197, v116, v117
	global_store_dwordx4 v167, v[194:197], s[20:21] offset:256
	v_mul_f32_e32 v202, v119, v119
	v_fmac_f32_e32 v202, v118, v118
	v_mul_f32_e32 v203, v121, v121
	v_fmac_f32_e32 v203, v120, v120
	v_mul_f32_e32 v204, v115, v115
	v_add_f32_e32 v202, v202, v203
	v_fmac_f32_e32 v204, v114, v114
	v_add_f32_e32 v202, v202, v204
	v_mul_f32_e32 v204, v117, v117
	v_fmac_f32_e32 v204, v116, v116
	v_add_f32_e32 v205, v204, v202
	v_add_f32_e32 v182, v201, v205
	v_mov_b32_e32 v183, v182
	s_nop 1
	v_permlane16_swap_b32_e32 v182, v183
	v_add_f32_e32 v182, v182, v183
	v_mov_b32_e32 v183, v182
	s_nop 1
	v_permlane32_swap_b32_e32 v182, v183
	s_and_saveexec_b64 s[24:25], s[40:41]
	v_add_f32_e32 v182, v182, v183
	v_mul_f32_e32 v182, 0x49800000, v182
	v_trunc_f32_e32 v182, v182
	v_mul_f32_e32 v183, 0x2f800000, v182
	v_floor_f32_e32 v183, v183
	v_fmac_f32_e32 v182, 0xcf800000, v183
	v_cvt_u32_f32_e32 v182, v182
	v_cvt_u32_f32_e32 v183, v183
	global_atomic_add_x2 v165, v[182:183], s[46:47]
	s_or_b64 exec, exec, s[24:25]
	s_nop 0
	v_add_u32_e32 v180, 0x100000, v164
	global_load_dwordx4 v[190:193], v180, s[14:15]
	global_load_dwordx4 v[194:197], v180, s[14:15] offset:16
	global_load_dwordx4 v[198:201], v180, s[14:15] offset:512
	global_load_dwordx4 v[202:205], v180, s[14:15] offset:528
	s_waitcnt vmcnt(19)
	v_pk_add_f32 v[110:111], v[110:111], v[206:207]
	v_pk_add_f32 v[112:113], v[112:113], v[208:209]
	v_pk_add_f32 v[106:107], v[106:107], v[210:211]
	v_pk_add_f32 v[108:109], v[108:109], v[212:213]
	v_pk_add_f32 v[102:103], v[102:103], v[214:215]
	v_pk_add_f32 v[104:105], v[104:105], v[216:217]
	v_pk_add_f32 v[98:99], v[98:99], v[218:219]
	v_pk_add_f32 v[100:101], v[100:101], v[220:221]
	v_add_u32_e32 v166, 0x20000, v164
	v_lshrrev_b32_e32 v167, 1, v166
	global_store_dwordx4 v166, v[110:113], s[30:31] nt
	global_store_dwordx4 v166, v[106:109], s[30:31] offset:16 nt
	v_cvt_pk_bf16_f32 v206, v110, v111
	v_cvt_pk_bf16_f32 v207, v112, v113
	v_cvt_pk_bf16_f32 v208, v106, v107
	v_cvt_pk_bf16_f32 v209, v108, v109
	global_store_dwordx4 v167, v[206:209], s[20:21]
	global_store_dwordx4 v166, v[102:105], s[30:31] offset:512 nt
	global_store_dwordx4 v166, v[98:101], s[30:31] offset:528 nt
	v_mul_f32_e32 v214, v111, v111
	v_fmac_f32_e32 v214, v110, v110
	v_mul_f32_e32 v215, v113, v113
	v_fmac_f32_e32 v215, v112, v112
	v_mul_f32_e32 v216, v107, v107
	v_add_f32_e32 v214, v214, v215
	v_fmac_f32_e32 v216, v106, v106
	v_add_f32_e32 v214, v214, v216
	v_mul_f32_e32 v216, v109, v109
	v_fmac_f32_e32 v216, v108, v108
	v_add_f32_e32 v217, v216, v214
	v_cvt_pk_bf16_f32 v210, v102, v103
	v_cvt_pk_bf16_f32 v211, v104, v105
	v_cvt_pk_bf16_f32 v212, v98, v99
	v_cvt_pk_bf16_f32 v213, v100, v101
	global_store_dwordx4 v167, v[210:213], s[20:21] offset:256
	v_mul_f32_e32 v218, v103, v103
	v_fmac_f32_e32 v218, v102, v102
	v_mul_f32_e32 v219, v105, v105
	v_fmac_f32_e32 v219, v104, v104
	v_mul_f32_e32 v220, v99, v99
	v_add_f32_e32 v218, v218, v219
	v_fmac_f32_e32 v220, v98, v98
	v_add_f32_e32 v218, v218, v220
	v_mul_f32_e32 v220, v101, v101
	v_fmac_f32_e32 v220, v100, v100
	v_add_f32_e32 v221, v220, v218
	v_add_f32_e32 v222, v217, v221
	v_mov_b32_e32 v223, v222
	s_nop 1
	v_permlane16_swap_b32_e32 v222, v223
	v_add_f32_e32 v222, v222, v223
	v_mov_b32_e32 v223, v222
	s_nop 1
	v_permlane32_swap_b32_e32 v222, v223
	s_and_saveexec_b64 s[24:25], s[40:41]
	v_add_f32_e32 v222, v222, v223
	v_mul_f32_e32 v222, 0x49800000, v222
	v_trunc_f32_e32 v222, v222
	v_mul_f32_e32 v223, 0x2f800000, v222
	v_floor_f32_e32 v223, v223
	v_fmac_f32_e32 v222, 0xcf800000, v223
	v_cvt_u32_f32_e32 v222, v222
	v_cvt_u32_f32_e32 v223, v223
	global_atomic_add_x2 v165, v[222:223], s[46:47] offset:128
	s_or_b64 exec, exec, s[24:25]
	s_nop 0
	v_add_u32_e32 v180, 0x120000, v164
	global_load_dwordx4 v[206:209], v180, s[14:15]
	global_load_dwordx4 v[210:213], v180, s[14:15] offset:16
	global_load_dwordx4 v[214:217], v180, s[14:15] offset:512
	global_load_dwordx4 v[218:221], v180, s[14:15] offset:528
	s_waitcnt vmcnt(26)
; __device__ __forceinline__ unsigned cvt_pk_bf16(float lo, float hi) { unsigned r; asm volatile("v_cvt_pk_bf16_f32 %0, %1, %2" : "=v"(r) : "v"(lo), "v"(hi)); return r; }
;     __device__ __forceinline__ void operator()(const f32x4 (&acc)[2][2][4][2], const Unit& u, int wr, int wc, int fr, int fq) const {
;     ...
;         for (int it = 0; it < 8; ++it) {
;             const int ai = it >> 2, m = it & 3;
;             const int row = row0 + ai * HALF + m * 16; float sq = 0.f;
;             const f32x4 cb0 = nb[0], cb1 = nb[1], cb2 = nb[2], cb3 = nb[3];
;             if (it < 7) { const size_t offn = (size_t)(row0 + ((it + 1) >> 2) * HALF + ((it + 1) & 3) * 16) * XD + col0;
;                 nb[0] = *(const f32x4*)(base + offn); nb[1] = *(const f32x4*)(base + offn + 4); nb[2] = *(const f32x4*)(base + offn + HALF); nb[3] = *(const f32x4*)(base + offn + HALF + 4); }
; #pragma unroll
;             for (int bj = 0; bj < 2; ++bj) {
;                 const size_t off = (size_t)row * XD + col0 + bj * HALF;
;                 const f32x4 v0 = acc[ai][bj][m][0] + (bj ? cb2 : cb0), v1 = acc[ai][bj][m][1] + (bj ? cb3 : cb1);
;                 if (out) { __builtin_nontemporal_store(v0, (f32x4*)(out + off)); __builtin_nontemporal_store(v1, (f32x4*)(out + off + 4)); }
;                 u32x4 w; w.x = cvt_pk_bf16(v0[0], v0[1]); w.y = cvt_pk_bf16(v0[2], v0[3]); w.z = cvt_pk_bf16(v1[0], v1[1]); w.w = cvt_pk_bf16(v1[2], v1[3]);
;                 if (xb) *(u32x4*)(xb + off) = w;
;                 sq += (v0[0] * v0[0] + v0[1] * v0[1]) + (v0[2] * v0[2] + v0[3] * v0[3]) + (v1[0] * v1[0] + v1[1] * v1[1]) + (v1[2] * v1[2] + v1[3] * v1[3]);
;             }
;             { const unsigned u1 = __float_as_uint(sq); auto r1 = __builtin_amdgcn_permlane16_swap(u1, u1, false, false); sq = __uint_as_float(r1[0]) + __uint_as_float(r1[1]);
;               const unsigned u2 = __float_as_uint(sq); auto r2 = __builtin_amdgcn_permlane32_swap(u2, u2, false, false); sq = __uint_as_float(r2[0]) + __uint_as_float(r2[1]); }
;             if (fq == 0) atomicAdd(ssn + row, (unsigned long long)(sq * SS_SCALE));
	v_pk_add_f32 v[94:95], v[94:95], v[130:131]
	v_pk_add_f32 v[96:97], v[96:97], v[132:133]
	v_pk_add_f32 v[90:91], v[90:91], v[134:135]
	v_pk_add_f32 v[92:93], v[92:93], v[136:137]
	v_pk_add_f32 v[86:87], v[86:87], v[138:139]
	v_pk_add_f32 v[88:89], v[88:89], v[140:141]
	v_pk_add_f32 v[82:83], v[82:83], v[142:143]
	v_pk_add_f32 v[84:85], v[84:85], v[144:145]
	v_add_u32_e32 v166, 0x40000, v164
	v_lshrrev_b32_e32 v167, 1, v166
	global_store_dwordx4 v166, v[94:97], s[30:31] nt
	global_store_dwordx4 v166, v[90:93], s[30:31] offset:16 nt
	v_cvt_pk_bf16_f32 v130, v94, v95
	v_cvt_pk_bf16_f32 v131, v96, v97
	v_cvt_pk_bf16_f32 v132, v90, v91
	v_cvt_pk_bf16_f32 v133, v92, v93
	global_store_dwordx4 v167, v[130:133], s[20:21]
	global_store_dwordx4 v166, v[86:89], s[30:31] offset:512 nt
	global_store_dwordx4 v166, v[82:85], s[30:31] offset:528 nt
	v_mul_f32_e32 v138, v95, v95
	v_fmac_f32_e32 v138, v94, v94
	v_mul_f32_e32 v139, v97, v97
	v_fmac_f32_e32 v139, v96, v96
	v_mul_f32_e32 v140, v91, v91
	v_add_f32_e32 v138, v138, v139
	v_fmac_f32_e32 v140, v90, v90
	v_add_f32_e32 v138, v138, v140
	v_mul_f32_e32 v140, v93, v93
	v_fmac_f32_e32 v140, v92, v92
	v_add_f32_e32 v141, v140, v138
	v_cvt_pk_bf16_f32 v134, v86, v87
	v_cvt_pk_bf16_f32 v135, v88, v89
	v_cvt_pk_bf16_f32 v136, v82, v83
	v_cvt_pk_bf16_f32 v137, v84, v85
	global_store_dwordx4 v167, v[134:137], s[20:21] offset:256
	v_mul_f32_e32 v142, v87, v87
	v_fmac_f32_e32 v142, v86, v86
	v_mul_f32_e32 v143, v89, v89
	v_fmac_f32_e32 v143, v88, v88
	v_mul_f32_e32 v144, v83, v83
	v_add_f32_e32 v142, v142, v143
	v_fmac_f32_e32 v144, v82, v82
	v_add_f32_e32 v142, v142, v144
	v_mul_f32_e32 v144, v85, v85
	v_fmac_f32_e32 v144, v84, v84
	v_add_f32_e32 v145, v144, v142
	v_add_f32_e32 v182, v141, v145
	v_mov_b32_e32 v183, v182
	s_nop 1
	v_permlane16_swap_b32_e32 v182, v183
	v_add_f32_e32 v182, v182, v183
	v_mov_b32_e32 v183, v182
	s_nop 1
	v_permlane32_swap_b32_e32 v182, v183
	s_and_saveexec_b64 s[24:25], s[40:41]
	v_add_f32_e32 v182, v182, v183
	v_mul_f32_e32 v182, 0x49800000, v182
	v_trunc_f32_e32 v182, v182
	v_mul_f32_e32 v183, 0x2f800000, v182
	v_floor_f32_e32 v183, v183
	v_fmac_f32_e32 v182, 0xcf800000, v183
	v_cvt_u32_f32_e32 v182, v182
	v_cvt_u32_f32_e32 v183, v183
	global_atomic_add_x2 v165, v[182:183], s[46:47] offset:256
	s_or_b64 exec, exec, s[24:25]
	s_nop 0
	v_add_u32_e32 v180, 0x140000, v164
	global_load_dwordx4 v[130:133], v180, s[14:15]
	global_load_dwordx4 v[134:137], v180, s[14:15] offset:16
	global_load_dwordx4 v[138:141], v180, s[14:15] offset:512
	global_load_dwordx4 v[142:145], v180, s[14:15] offset:528
	s_waitcnt vmcnt(33)
	v_pk_add_f32 v[78:79], v[78:79], v[146:147]
	v_pk_add_f32 v[80:81], v[80:81], v[148:149]
	v_pk_add_f32 v[74:75], v[74:75], v[150:151]
	v_pk_add_f32 v[76:77], v[76:77], v[152:153]
	v_pk_add_f32 v[70:71], v[70:71], v[232:233]
	v_pk_add_f32 v[72:73], v[72:73], v[234:235]
	v_pk_add_f32 v[66:67], v[66:67], v[236:237]
	v_pk_add_f32 v[68:69], v[68:69], v[238:239]
	v_add_u32_e32 v166, 0x60000, v164
	v_lshrrev_b32_e32 v167, 1, v166
	global_store_dwordx4 v166, v[78:81], s[30:31] nt
	global_store_dwordx4 v166, v[74:77], s[30:31] offset:16 nt
	v_cvt_pk_bf16_f32 v146, v78, v79
	v_cvt_pk_bf16_f32 v147, v80, v81
	v_cvt_pk_bf16_f32 v148, v74, v75
	v_cvt_pk_bf16_f32 v149, v76, v77
	global_store_dwordx4 v167, v[146:149], s[20:21]
	global_store_dwordx4 v166, v[70:73], s[30:31] offset:512 nt
	global_store_dwordx4 v166, v[66:69], s[30:31] offset:528 nt
	v_mul_f32_e32 v232, v79, v79
	v_fmac_f32_e32 v232, v78, v78
	v_mul_f32_e32 v233, v81, v81
	v_fmac_f32_e32 v233, v80, v80
	v_mul_f32_e32 v234, v75, v75
	v_add_f32_e32 v232, v232, v233
	v_fmac_f32_e32 v234, v74, v74
	v_add_f32_e32 v232, v232, v234
	v_mul_f32_e32 v234, v77, v77
	v_fmac_f32_e32 v234, v76, v76
	v_add_f32_e32 v235, v234, v232
	v_cvt_pk_bf16_f32 v150, v70, v71
	v_cvt_pk_bf16_f32 v151, v72, v73
	v_cvt_pk_bf16_f32 v152, v66, v67
	v_cvt_pk_bf16_f32 v153, v68, v69
	global_store_dwordx4 v167, v[150:153], s[20:21] offset:256
	v_mul_f32_e32 v236, v71, v71
	v_fmac_f32_e32 v236, v70, v70
	v_mul_f32_e32 v237, v73, v73
	v_fmac_f32_e32 v237, v72, v72
	v_mul_f32_e32 v238, v67, v67
	v_add_f32_e32 v236, v236, v237
	v_fmac_f32_e32 v238, v66, v66
	v_add_f32_e32 v236, v236, v238
	v_mul_f32_e32 v238, v69, v69
	v_fmac_f32_e32 v238, v68, v68
	v_add_f32_e32 v239, v238, v236
	v_add_f32_e32 v222, v235, v239
	v_mov_b32_e32 v223, v222
	s_nop 1
	v_permlane16_swap_b32_e32 v222, v223
	v_add_f32_e32 v222, v222, v223
	v_mov_b32_e32 v223, v222
	s_nop 1
	v_permlane32_swap_b32_e32 v222, v223
	s_and_saveexec_b64 s[24:25], s[40:41]
	v_add_f32_e32 v222, v222, v223
	v_mul_f32_e32 v222, 0x49800000, v222
	v_trunc_f32_e32 v222, v222
	v_mul_f32_e32 v223, 0x2f800000, v222
	v_floor_f32_e32 v223, v223
	v_fmac_f32_e32 v222, 0xcf800000, v223
	v_cvt_u32_f32_e32 v222, v222
	v_cvt_u32_f32_e32 v223, v223
	global_atomic_add_x2 v165, v[222:223], s[46:47] offset:384
	s_or_b64 exec, exec, s[24:25]
	s_nop 0
	v_add_u32_e32 v180, 0x160000, v164
	global_load_dwordx4 v[146:149], v180, s[14:15]
	global_load_dwordx4 v[150:153], v180, s[14:15] offset:16
	global_load_dwordx4 v[232:235], v180, s[14:15] offset:512
	global_load_dwordx4 v[236:239], v180, s[14:15] offset:528
	s_waitcnt vmcnt(33)
; __device__ __forceinline__ unsigned cvt_pk_bf16(float lo, float hi) { unsigned r; asm volatile("v_cvt_pk_bf16_f32 %0, %1, %2" : "=v"(r) : "v"(lo), "v"(hi)); return r; }
;     __device__ __forceinline__ void operator()(const f32x4 (&acc)[2][2][4][2], const Unit& u, int wr, int wc, int fr, int fq) const {
;     ...
;         for (int it = 0; it < 8; ++it) {
;             const int ai = it >> 2, m = it & 3;
;             const int row = row0 + ai * HALF + m * 16; float sq = 0.f;
;             const f32x4 cb0 = nb[0], cb1 = nb[1], cb2 = nb[2], cb3 = nb[3];
;             if (it < 7) { const size_t offn = (size_t)(row0 + ((it + 1) >> 2) * HALF + ((it + 1) & 3) * 16) * XD + col0;
;                 nb[0] = *(const f32x4*)(base + offn); nb[1] = *(const f32x4*)(base + offn + 4); nb[2] = *(const f32x4*)(base + offn + HALF); nb[3] = *(const f32x4*)(base + offn + HALF + 4); }
; #pragma unroll
;             for (int bj = 0; bj < 2; ++bj) {
;                 const size_t off = (size_t)row * XD + col0 + bj * HALF;
;                 const f32x4 v0 = acc[ai][bj][m][0] + (bj ? cb2 : cb0), v1 = acc[ai][bj][m][1] + (bj ? cb3 : cb1);
;                 if (out) { __builtin_nontemporal_store(v0, (f32x4*)(out + off)); __builtin_nontemporal_store(v1, (f32x4*)(out + off + 4)); }
;                 u32x4 w; w.x = cvt_pk_bf16(v0[0], v0[1]); w.y = cvt_pk_bf16(v0[2], v0[3]); w.z = cvt_pk_bf16(v1[0], v1[1]); w.w = cvt_pk_bf16(v1[2], v1[3]);
;                 if (xb) *(u32x4*)(xb + off) = w;
;                 sq += (v0[0] * v0[0] + v0[1] * v0[1]) + (v0[2] * v0[2] + v0[3] * v0[3]) + (v1[0] * v1[0] + v1[1] * v1[1]) + (v1[2] * v1[2] + v1[3] * v1[3]);
;             }
;             { const unsigned u1 = __float_as_uint(sq); auto r1 = __builtin_amdgcn_permlane16_swap(u1, u1, false, false); sq = __uint_as_float(r1[0]) + __uint_as_float(r1[1]);
;               const unsigned u2 = __float_as_uint(sq); auto r2 = __builtin_amdgcn_permlane32_swap(u2, u2, false, false); sq = __uint_as_float(r2[0]) + __uint_as_float(r2[1]); }
;             if (fq == 0) atomicAdd(ssn + row, (unsigned long long)(sq * SS_SCALE));
	v_pk_add_f32 v[62:63], v[62:63], v[190:191]
	v_pk_add_f32 v[64:65], v[64:65], v[192:193]
	v_pk_add_f32 v[58:59], v[58:59], v[194:195]
	v_pk_add_f32 v[60:61], v[60:61], v[196:197]
	v_pk_add_f32 v[54:55], v[54:55], v[198:199]
	v_pk_add_f32 v[56:57], v[56:57], v[200:201]
	v_pk_add_f32 v[50:51], v[50:51], v[202:203]
	v_pk_add_f32 v[52:53], v[52:53], v[204:205]
	v_add_u32_e32 v166, 0x100000, v164
	v_lshrrev_b32_e32 v167, 1, v166
	global_store_dwordx4 v166, v[62:65], s[30:31] nt
	global_store_dwordx4 v166, v[58:61], s[30:31] offset:16 nt
	v_cvt_pk_bf16_f32 v190, v62, v63
	v_cvt_pk_bf16_f32 v191, v64, v65
	v_cvt_pk_bf16_f32 v192, v58, v59
	v_cvt_pk_bf16_f32 v193, v60, v61
	global_store_dwordx4 v167, v[190:193], s[20:21]
	global_store_dwordx4 v166, v[54:57], s[30:31] offset:512 nt
	global_store_dwordx4 v166, v[50:53], s[30:31] offset:528 nt
	v_mul_f32_e32 v198, v63, v63
	v_fmac_f32_e32 v198, v62, v62
	v_mul_f32_e32 v199, v65, v65
	v_fmac_f32_e32 v199, v64, v64
	v_mul_f32_e32 v200, v59, v59
	v_add_f32_e32 v198, v198, v199
	v_fmac_f32_e32 v200, v58, v58
	v_add_f32_e32 v198, v198, v200
	v_mul_f32_e32 v200, v61, v61
	v_fmac_f32_e32 v200, v60, v60
	v_add_f32_e32 v201, v200, v198
	v_cvt_pk_bf16_f32 v194, v54, v55
	v_cvt_pk_bf16_f32 v195, v56, v57
	v_cvt_pk_bf16_f32 v196, v50, v51
	v_cvt_pk_bf16_f32 v197, v52, v53
	global_store_dwordx4 v167, v[194:197], s[20:21] offset:256
	v_mul_f32_e32 v202, v55, v55
	v_fmac_f32_e32 v202, v54, v54
	v_mul_f32_e32 v203, v57, v57
	v_fmac_f32_e32 v203, v56, v56
	v_mul_f32_e32 v204, v51, v51
	v_add_f32_e32 v202, v202, v203
	v_fmac_f32_e32 v204, v50, v50
	v_add_f32_e32 v202, v202, v204
	v_mul_f32_e32 v204, v53, v53
	v_fmac_f32_e32 v204, v52, v52
	v_add_f32_e32 v205, v204, v202
	v_add_f32_e32 v182, v201, v205
	v_mov_b32_e32 v183, v182
	s_nop 1
	v_permlane16_swap_b32_e32 v182, v183
	v_add_f32_e32 v182, v182, v183
	v_mov_b32_e32 v183, v182
	s_nop 1
	v_permlane32_swap_b32_e32 v182, v183
	s_and_saveexec_b64 s[24:25], s[40:41]
	v_add_f32_e32 v182, v182, v183
	v_mul_f32_e32 v182, 0x49800000, v182
	v_trunc_f32_e32 v182, v182
	v_mul_f32_e32 v183, 0x2f800000, v182
	v_floor_f32_e32 v183, v183
	v_fmac_f32_e32 v182, 0xcf800000, v183
	v_cvt_u32_f32_e32 v182, v182
	v_cvt_u32_f32_e32 v183, v183
	global_atomic_add_x2 v165, v[182:183], s[46:47] offset:1024
	s_or_b64 exec, exec, s[24:25]
	s_waitcnt vmcnt(29)
	v_pk_add_f32 v[46:47], v[46:47], v[206:207]
	v_pk_add_f32 v[48:49], v[48:49], v[208:209]
	v_pk_add_f32 v[42:43], v[42:43], v[210:211]
	v_pk_add_f32 v[44:45], v[44:45], v[212:213]
	v_pk_add_f32 v[38:39], v[38:39], v[214:215]
	v_pk_add_f32 v[40:41], v[40:41], v[216:217]
	v_pk_add_f32 v[34:35], v[34:35], v[218:219]
	v_pk_add_f32 v[36:37], v[36:37], v[220:221]
	v_add_u32_e32 v166, 0x120000, v164
	v_lshrrev_b32_e32 v167, 1, v166
	global_store_dwordx4 v166, v[46:49], s[30:31] nt
	global_store_dwordx4 v166, v[42:45], s[30:31] offset:16 nt
	v_cvt_pk_bf16_f32 v206, v46, v47
	v_cvt_pk_bf16_f32 v207, v48, v49
	v_cvt_pk_bf16_f32 v208, v42, v43
	v_cvt_pk_bf16_f32 v209, v44, v45
	global_store_dwordx4 v167, v[206:209], s[20:21]
	global_store_dwordx4 v166, v[38:41], s[30:31] offset:512 nt
	global_store_dwordx4 v166, v[34:37], s[30:31] offset:528 nt
	v_mul_f32_e32 v214, v47, v47
	v_fmac_f32_e32 v214, v46, v46
	v_mul_f32_e32 v215, v49, v49
	v_fmac_f32_e32 v215, v48, v48
	v_mul_f32_e32 v216, v43, v43
	v_add_f32_e32 v214, v214, v215
	v_fmac_f32_e32 v216, v42, v42
	v_add_f32_e32 v214, v214, v216
	v_mul_f32_e32 v216, v45, v45
	v_fmac_f32_e32 v216, v44, v44
	v_add_f32_e32 v217, v216, v214
	v_cvt_pk_bf16_f32 v210, v38, v39
	v_cvt_pk_bf16_f32 v211, v40, v41
	v_cvt_pk_bf16_f32 v212, v34, v35
	v_cvt_pk_bf16_f32 v213, v36, v37
	global_store_dwordx4 v167, v[210:213], s[20:21] offset:256
	v_mul_f32_e32 v218, v39, v39
	v_fmac_f32_e32 v218, v38, v38
	v_mul_f32_e32 v219, v41, v41
	v_fmac_f32_e32 v219, v40, v40
	v_mul_f32_e32 v220, v35, v35
	v_add_f32_e32 v218, v218, v219
	v_fmac_f32_e32 v220, v34, v34
	v_add_f32_e32 v218, v218, v220
	v_mul_f32_e32 v220, v37, v37
	v_fmac_f32_e32 v220, v36, v36
	v_add_f32_e32 v221, v220, v218
	v_add_f32_e32 v222, v217, v221
	v_mov_b32_e32 v223, v222
	s_nop 1
	v_permlane16_swap_b32_e32 v222, v223
	v_add_f32_e32 v222, v222, v223
	v_mov_b32_e32 v223, v222
	s_nop 1
	v_permlane32_swap_b32_e32 v222, v223
	s_and_saveexec_b64 s[24:25], s[40:41]
	v_add_f32_e32 v222, v222, v223
	v_mul_f32_e32 v222, 0x49800000, v222
	v_trunc_f32_e32 v222, v222
	v_mul_f32_e32 v223, 0x2f800000, v222
	v_floor_f32_e32 v223, v223
	v_fmac_f32_e32 v222, 0xcf800000, v223
	v_cvt_u32_f32_e32 v222, v222
	v_cvt_u32_f32_e32 v223, v223
	global_atomic_add_x2 v165, v[222:223], s[46:47] offset:1152
	s_or_b64 exec, exec, s[24:25]
	s_waitcnt vmcnt(25)
; __device__ __forceinline__ unsigned cvt_pk_bf16(float lo, float hi) { unsigned r; asm volatile("v_cvt_pk_bf16_f32 %0, %1, %2" : "=v"(r) : "v"(lo), "v"(hi)); return r; }
;     __device__ __forceinline__ void operator()(const f32x4 (&acc)[2][2][4][2], const Unit& u, int wr, int wc, int fr, int fq) const {
;     ...
;         for (int it = 0; it < 8; ++it) {
;             const int ai = it >> 2, m = it & 3;
;             const int row = row0 + ai * HALF + m * 16; float sq = 0.f;
;             const f32x4 cb0 = nb[0], cb1 = nb[1], cb2 = nb[2], cb3 = nb[3];
;             if (it < 7) { const size_t offn = (size_t)(row0 + ((it + 1) >> 2) * HALF + ((it + 1) & 3) * 16) * XD + col0;
;                 nb[0] = *(const f32x4*)(base + offn); nb[1] = *(const f32x4*)(base + offn + 4); nb[2] = *(const f32x4*)(base + offn + HALF); nb[3] = *(const f32x4*)(base + offn + HALF + 4); }
; #pragma unroll
;             for (int bj = 0; bj < 2; ++bj) {
;                 const size_t off = (size_t)row * XD + col0 + bj * HALF;
;                 const f32x4 v0 = acc[ai][bj][m][0] + (bj ? cb2 : cb0), v1 = acc[ai][bj][m][1] + (bj ? cb3 : cb1);
;                 if (out) { __builtin_nontemporal_store(v0, (f32x4*)(out + off)); __builtin_nontemporal_store(v1, (f32x4*)(out + off + 4)); }
;                 u32x4 w; w.x = cvt_pk_bf16(v0[0], v0[1]); w.y = cvt_pk_bf16(v0[2], v0[3]); w.z = cvt_pk_bf16(v1[0], v1[1]); w.w = cvt_pk_bf16(v1[2], v1[3]);
;                 if (xb) *(u32x4*)(xb + off) = w;
;                 sq += (v0[0] * v0[0] + v0[1] * v0[1]) + (v0[2] * v0[2] + v0[3] * v0[3]) + (v1[0] * v1[0] + v1[1] * v1[1]) + (v1[2] * v1[2] + v1[3] * v1[3]);
;             }
;             { const unsigned u1 = __float_as_uint(sq); auto r1 = __builtin_amdgcn_permlane16_swap(u1, u1, false, false); sq = __uint_as_float(r1[0]) + __uint_as_float(r1[1]);
;               const unsigned u2 = __float_as_uint(sq); auto r2 = __builtin_amdgcn_permlane32_swap(u2, u2, false, false); sq = __uint_as_float(r2[0]) + __uint_as_float(r2[1]); }
;             if (fq == 0) atomicAdd(ssn + row, (unsigned long long)(sq * SS_SCALE));
	v_pk_add_f32 v[30:31], v[30:31], v[130:131]
	v_pk_add_f32 v[32:33], v[32:33], v[132:133]
	v_pk_add_f32 v[26:27], v[26:27], v[134:135]
	v_pk_add_f32 v[28:29], v[28:29], v[136:137]
	v_pk_add_f32 v[22:23], v[22:23], v[138:139]
	v_pk_add_f32 v[24:25], v[24:25], v[140:141]
	v_pk_add_f32 v[18:19], v[18:19], v[142:143]
	v_pk_add_f32 v[20:21], v[20:21], v[144:145]
	v_add_u32_e32 v166, 0x140000, v164
	v_lshrrev_b32_e32 v167, 1, v166
	global_store_dwordx4 v166, v[30:33], s[30:31] nt
	global_store_dwordx4 v166, v[26:29], s[30:31] offset:16 nt
	v_cvt_pk_bf16_f32 v130, v30, v31
	v_cvt_pk_bf16_f32 v131, v32, v33
	v_cvt_pk_bf16_f32 v132, v26, v27
	v_cvt_pk_bf16_f32 v133, v28, v29
	global_store_dwordx4 v167, v[130:133], s[20:21]
	global_store_dwordx4 v166, v[22:25], s[30:31] offset:512 nt
	global_store_dwordx4 v166, v[18:21], s[30:31] offset:528 nt
	v_mul_f32_e32 v138, v31, v31
	v_fmac_f32_e32 v138, v30, v30
	v_mul_f32_e32 v139, v33, v33
	v_fmac_f32_e32 v139, v32, v32
	v_mul_f32_e32 v140, v27, v27
	v_add_f32_e32 v138, v138, v139
	v_fmac_f32_e32 v140, v26, v26
	v_add_f32_e32 v138, v138, v140
	v_mul_f32_e32 v140, v29, v29
	v_fmac_f32_e32 v140, v28, v28
	v_add_f32_e32 v141, v140, v138
	v_cvt_pk_bf16_f32 v134, v22, v23
	v_cvt_pk_bf16_f32 v135, v24, v25
	v_cvt_pk_bf16_f32 v136, v18, v19
	v_cvt_pk_bf16_f32 v137, v20, v21
	global_store_dwordx4 v167, v[134:137], s[20:21] offset:256
	v_mul_f32_e32 v142, v23, v23
	v_fmac_f32_e32 v142, v22, v22
	v_mul_f32_e32 v143, v25, v25
	v_fmac_f32_e32 v143, v24, v24
	v_mul_f32_e32 v144, v19, v19
	v_add_f32_e32 v142, v142, v143
	v_fmac_f32_e32 v144, v18, v18
	v_add_f32_e32 v142, v142, v144
	v_mul_f32_e32 v144, v21, v21
	v_fmac_f32_e32 v144, v20, v20
	v_add_f32_e32 v145, v144, v142
	v_add_f32_e32 v182, v141, v145
	v_mov_b32_e32 v183, v182
	s_nop 1
	v_permlane16_swap_b32_e32 v182, v183
	v_add_f32_e32 v182, v182, v183
	v_mov_b32_e32 v183, v182
	s_nop 1
	v_permlane32_swap_b32_e32 v182, v183
	s_and_saveexec_b64 s[24:25], s[40:41]
	v_add_f32_e32 v182, v182, v183
	v_mul_f32_e32 v182, 0x49800000, v182
	v_trunc_f32_e32 v182, v182
	v_mul_f32_e32 v183, 0x2f800000, v182
	v_floor_f32_e32 v183, v183
	v_fmac_f32_e32 v182, 0xcf800000, v183
	v_cvt_u32_f32_e32 v182, v182
	v_cvt_u32_f32_e32 v183, v183
	global_atomic_add_x2 v165, v[182:183], s[46:47] offset:1280
	s_or_b64 exec, exec, s[24:25]
	s_waitcnt vmcnt(21)
	v_pk_add_f32 v[14:15], v[14:15], v[146:147]
	v_pk_add_f32 v[16:17], v[16:17], v[148:149]
	v_pk_add_f32 v[10:11], v[10:11], v[150:151]
	v_pk_add_f32 v[12:13], v[12:13], v[152:153]
	v_pk_add_f32 v[6:7], v[6:7], v[232:233]
	v_pk_add_f32 v[8:9], v[8:9], v[234:235]
	v_pk_add_f32 v[2:3], v[2:3], v[236:237]
	v_pk_add_f32 v[4:5], v[4:5], v[238:239]
	v_add_u32_e32 v166, 0x160000, v164
	v_lshrrev_b32_e32 v167, 1, v166
	global_store_dwordx4 v166, v[14:17], s[30:31] nt
	global_store_dwordx4 v166, v[10:13], s[30:31] offset:16 nt
	v_cvt_pk_bf16_f32 v146, v14, v15
	v_cvt_pk_bf16_f32 v147, v16, v17
	v_cvt_pk_bf16_f32 v148, v10, v11
	v_cvt_pk_bf16_f32 v149, v12, v13
	global_store_dwordx4 v167, v[146:149], s[20:21]
	global_store_dwordx4 v166, v[6:9], s[30:31] offset:512 nt
	global_store_dwordx4 v166, v[2:5], s[30:31] offset:528 nt
	v_mul_f32_e32 v232, v15, v15
	v_fmac_f32_e32 v232, v14, v14
	v_mul_f32_e32 v233, v17, v17
	v_fmac_f32_e32 v233, v16, v16
	v_mul_f32_e32 v234, v11, v11
	v_add_f32_e32 v232, v232, v233
	v_fmac_f32_e32 v234, v10, v10
	v_add_f32_e32 v232, v232, v234
	v_mul_f32_e32 v234, v13, v13
	v_fmac_f32_e32 v234, v12, v12
	v_add_f32_e32 v235, v234, v232
	v_cvt_pk_bf16_f32 v150, v6, v7
	v_cvt_pk_bf16_f32 v151, v8, v9
	v_cvt_pk_bf16_f32 v152, v2, v3
	v_cvt_pk_bf16_f32 v153, v4, v5
	global_store_dwordx4 v167, v[150:153], s[20:21] offset:256
	v_mul_f32_e32 v236, v7, v7
	v_fmac_f32_e32 v236, v6, v6
	v_mul_f32_e32 v237, v9, v9
	v_fmac_f32_e32 v237, v8, v8
	v_mul_f32_e32 v238, v3, v3
	v_add_f32_e32 v236, v236, v237
	v_fmac_f32_e32 v238, v2, v2
	v_add_f32_e32 v236, v236, v238
	v_mul_f32_e32 v238, v5, v5
	v_fmac_f32_e32 v238, v4, v4
	v_add_f32_e32 v239, v238, v236
	v_add_f32_e32 v222, v235, v239
	v_mov_b32_e32 v223, v222
	s_nop 1
	v_permlane16_swap_b32_e32 v222, v223
	v_add_f32_e32 v222, v222, v223
	v_mov_b32_e32 v223, v222
	s_nop 1
	v_permlane32_swap_b32_e32 v222, v223
	s_and_saveexec_b64 s[24:25], s[40:41]
	v_add_f32_e32 v222, v222, v223
	v_mul_f32_e32 v222, 0x49800000, v222
	v_trunc_f32_e32 v222, v222
	v_mul_f32_e32 v223, 0x2f800000, v222
	v_floor_f32_e32 v223, v223
	v_fmac_f32_e32 v222, 0xcf800000, v223
	v_cvt_u32_f32_e32 v222, v222
	v_cvt_u32_f32_e32 v223, v223
	global_atomic_add_x2 v165, v[222:223], s[46:47] offset:1408
	s_or_b64 exec, exec, s[24:25]
	s_branch .Lepires_done

; #define PG8_BAR __builtin_amdgcn_s_barrier()
; template <class Epi, class Sched, bool ALIGN_EPI = false, bool SP2 = false>
; __device__ __forceinline__ void gemm_phase(PG8_LAS unsigned char* lds, const Gemm g, const Sched& S, const Epi& E) {
;     ...
;         if constexpr (!Epi::AFTER_DRAIN) { E(acc, cur, wr, wc, fr, fq); S.done(cur); }
;         if (!has_next) break;
; #pragma unroll
;         for (int a = 0; a < 2; ++a)
; #pragma unroll
;             for (int b = 0; b < 2; ++b)
; #pragma unroll
;                 for (int m = 0; m < 4; ++m)
; #pragma unroll
;                     for (int n = 0; n < 2; ++n) acc[a][b][m][n] = (f32x4){0.f, 0.f, 0.f, 0.f};
;         cur = nxt; cA = nA; cB = nB; ++ui;
;         if constexpr (ALIGN_EPI) { if (wr == 1) PG8_BAR; }
.Lepires_done:
	s_andn2_b64 vcc, exec, s[42:43]
	s_mov_b64 s[24:25], -1
	s_cbranch_vccnz .LBB0_1419
	s_andn2_b64 vcc, exec, s[0:1]
	s_cbranch_vccnz .LBB0_1418
	s_barrier
	s_branch .LBB0_1418
